# P8: each workgroup runs its sample K-piece before its prompt tile, so the f32 partial stores drain under the prompt tile's K loop instead of in front of the grid barrier
# baseline (speedup 1.0000x reference)
; #define PG8_STAGE(bufoff, gbase, voff) do { _Pragma("unroll") for (int _i = 0; _i < 2; ++_i) \
;         __builtin_amdgcn_global_load_lds((const unsigned*)((const char*)(gbase) + (voff)[_i]), (LAS unsigned*)(lds + (bufoff) + ldsw + _i * 8192), 16, 0, 0); } while (0)
; template <class Epi, class S_t>
; __device__ __forceinline__ void gemm_phase(LAS unsigned char* lds, int lda, int ldb, const S_t& S, const Epi& E) {
;     ...
;     for (int i = 0; i < 2; ++i) { int R, C; stage_rc(tid * 16 + i * 8192, R, C); const int Rb = Epi::PERM ? ((R & ~31) + perm32(R & 31)) : R;
;         voffA[i] = (unsigned)(R * lda + C) * 2u; voffB[i] = (unsigned)(Rb * ldb + C) * 2u; }
;     const size_t kstep = (size_t)(BK * 2);
;     const size_t hstepA = (size_t)HALF * lda * 2, hstepB = (size_t)HALF * ldb * 2;
;     const unsigned ldsw = (unsigned)wid * 1024u;
;     const int aoff = lds_byte(wr * 64 + fr, fq * 8), boff = lds_byte(wc * 32 + fr, fq * 8);
;     ...
;     Unit cur, nxt; int ui = 0;
;     if (!S.next(0, cur)) return;
;     f32x4 acc[2][2][4][2];
; #pragma unroll
;     for (int a = 0; a < 2; ++a)
; #pragma unroll
;         for (int b = 0; b < 2; ++b)
; #pragma unroll
;             for (int m = 0; m < 4; ++m)
; #pragma unroll
;                 for (int n = 0; n < 2; ++n) acc[a][b][m][n] = (f32x4){0.f, 0.f, 0.f, 0.f};
;     bf16x8 At[4][2], B0[2][2], B1[2][2];
;     const char* cA = cur.A; const char* cB = cur.B;
;     PG8_STAGE(PG8_SB(0, 0), cB, voffB); PG8_STAGE(PG8_SA(0, 0), cA, voffA); PG8_STAGE(PG8_SB(0, 1), cB + hstepB, voffB); PG8_STAGE(PG8_SA(0, 1), cA + hstepA, voffA);
;     if (wr == 1) PG8_BAR;
;     PG8_WAIT_V(4); PG8_BAR;
;     PG8_STAGE(PG8_SB(1, 0), cB + kstep, voffB); PG8_STAGE(PG8_SA(1, 0), cA + kstep, voffA); PG8_STAGE(PG8_SB(1, 1), cB + hstepB + kstep, voffB);
;     PG8_WAIT_V(6); PG8_BAR;
;     __device__ __forceinline__ bool next(int i, Unit& u) const {
;     ...
;         const int tile = base.c >> 3, kz = base.c & 7;
;         if (kz < kz_lo || kz >= kz_hi) return false;
;         const int k = kz - kz_lo; int koff, nt;
;         if (mode == 0) { koff = k * ntp; nt = ntp; } else { koff = k < 4 ? 6 * k : 24 + 4 * (k - 4); nt = k < 4 ? 6 : 4; }
;         u.pm = 32 + (tile >> 3); u.pn = tile & 7; u.tag = 1 + kz; u.nt = nt;
;         u.A = base.A + (size_t)u.pm * base.a_tile + (size_t)koff * 128; u.B = base.B + (size_t)u.pn * base.b_tile + (size_t)koff * 128; return true;
.LBB0_1043:
	v_ashrrev_i32_e32 v1, 31, v11
	v_lshrrev_b32_e32 v1, 26, v1
	v_add_u32_e32 v1, v11, v1
	v_ashrrev_i32_e32 v8, 6, v1
	v_bfe_i32 v1, v11, 27, 1
	v_lshlrev_b32_e32 v0, 4, v11
	v_lshrrev_b32_e32 v1, 22, v1
	v_add_u32_e32 v1, v0, v1
	v_and_b32_e32 v1, 0xfffffc00, v1
	v_sub_u32_e32 v1, v0, v1
	v_lshrrev_b32_e32 v2, 4, v1
	v_bitop3_b32 v1, v2, v1, 32 bitop3:0x6c
	v_ashrrev_i32_e32 v3, 31, v1
	v_lshrrev_b32_e32 v3, 26, v3
	v_add_u32_e32 v3, v1, v3
	v_lshlrev_b32_e32 v2, 3, v8
	v_ashrrev_i32_e32 v9, 6, v3
	v_and_b32_e32 v3, 0xc0, v3
	v_and_b32_e32 v2, -16, v2
	v_sub_u32_e32 v1, v1, v3
	v_mov_b32_e32 v3, 1
	v_add_u32_e32 v2, v9, v2
	v_ashrrev_i16_sdwa v1, v3, sext(v1) dst_sel:DWORD dst_unused:UNUSED_PAD src0_sel:DWORD src1_sel:BYTE_0
	s_ashr_i32 s9, s5, 3
	v_lshlrev_b32_e32 v4, 5, v8
	v_bfe_i32 v10, v1, 0, 16
	v_lshlrev_b32_e32 v1, 1, v2
	v_lshrrev_b32_e32 v5, 2, v2
	v_and_b32_e32 v6, 3, v9
	s_mov_b32 s5, 0xfffe0
	v_and_b32_e32 v4, 32, v4
	v_and_b32_e32 v1, 24, v1
	v_and_b32_e32 v5, 4, v5
	v_and_or_b32 v6, v2, s5, v6
	s_add_u32 s0, s84, 0x6500000
	v_or3_b32 v1, v6, v5, v1
	v_add_lshl_u32 v4, v4, v10, 1
	v_add_u32_e32 v0, 0x2000, v0
	s_addc_u32 s1, s85, 0
	v_lshl_add_u32 v130, v1, 12, v4
	v_ashrrev_i32_e32 v1, 31, v0
	s_add_i32 s8, s8, s9
	v_lshrrev_b32_e32 v1, 22, v1
	s_ashr_i32 s9, s8, 31
	v_add_u32_e32 v1, v0, v1
	s_lshr_b32 s9, s9, 26
	v_ashrrev_i32_e32 v12, 10, v1
	s_add_i32 s9, s8, s9
	v_mul_i32_i24_e32 v1, 0x400, v12
	s_ashr_i32 s13, s9, 6
	s_andn2_b32 s9, s9, 63
	v_sub_u32_e32 v0, v0, v1
	s_sub_i32 s8, s8, s9
	v_lshrrev_b32_e32 v1, 4, v0
	s_bfe_i32 s9, s8, 0x80000
	v_bitop3_b32 v0, v1, v0, 32 bitop3:0x6c
	s_bfe_u32 s9, s9, 0x3000c
	v_lshl_add_u32 v128, v2, 12, v4
	v_ashrrev_i32_e32 v2, 31, v0
	s_add_i32 s9, s8, s9
	v_lshrrev_b32_e32 v2, 26, v2
	s_bfe_i32 s14, s9, 0x80000
	s_and_b32 s9, s9, 0xf8
	v_add_u32_e32 v2, v0, v2
	s_sub_i32 s8, s8, s9
	v_lshlrev_b32_e32 v1, 3, v12
	v_ashrrev_i32_e32 v13, 6, v2
	v_and_b32_e32 v2, 0xc0, v2
	s_lshl_b32 s13, s13, 3
	s_sext_i32_i8 s8, s8
	v_and_b32_e32 v1, -16, v1
	v_sub_u32_e32 v0, v0, v2
	s_add_i32 s8, s13, s8
	v_add_u32_e32 v1, v13, v1
	v_ashrrev_i16_sdwa v0, v3, sext(v0) dst_sel:DWORD dst_unused:UNUSED_PAD src0_sel:DWORD src1_sel:BYTE_0
	v_and_b32_e32 v3, 3, v13
	s_ashr_i32 s12, s4, 6
	s_sext_i32_i16 s14, s14
	s_ashr_i32 s9, s8, 31
	s_ashr_i32 s15, s4, 8
	v_and_or_b32 v3, v1, s5, v3
	s_lshl_b32 s5, s12, 10
	s_lshr_b32 s14, s14, 3
	s_lshl_b64 s[16:17], s[8:9], 20
	s_add_u32 s60, s44, s16
	s_addc_u32 s61, s45, s17
	s_bfe_i64 s[16:17], s[14:15], 0x100000
	s_lshl_b64 s[16:17], s[16:17], 20
	v_lshlrev_b32_e32 v4, 5, v12
	v_bfe_i32 v14, v0, 0, 16
	v_lshlrev_b32_e32 v0, 1, v1
	v_lshrrev_b32_e32 v2, 2, v1
	s_add_u32 s62, s0, s16
	v_and_b32_e32 v4, 32, v4
	v_and_b32_e32 v0, 24, v0
	v_and_b32_e32 v2, 4, v2
	s_addc_u32 s63, s1, s17
	s_mov_b64 s[98:99], s[60:61]
	s_mov_b64 s[100:101], s[62:63]
	v_readlane_b32 s20, v255, 14
	s_ashr_i32 s18, s2, 6
	s_add_i32 s18, s18, 32
	s_ashr_i32 s19, s18, 31
	s_lshl_b64 s[18:19], s[18:19], 20
	s_add_u32 s60, s44, s18
	s_addc_u32 s61, s45, s19
	s_lshl_b32 s20, s20, 9
	s_add_u32 s60, s60, s20
	s_addc_u32 s61, s61, 0
	s_bfe_u32 s21, s2, 0x30003
	s_lshl_b32 s21, s21, 20
	s_add_u32 s62, s0, s21
	s_addc_u32 s63, s1, 0
	s_add_u32 s62, s62, s20
	s_addc_u32 s63, s63, 0
	s_add_i32 s16, s5, 0
	v_or3_b32 v0, v3, v2, v0
	v_add_lshl_u32 v2, v4, v14, 1
	s_add_i32 m0, s16, 0x10000
	v_lshl_add_u32 v134, v0, 12, v2
	global_load_lds_dwordx4 v130, s[62:63]
	s_add_i32 m0, s16, 0x12000
	s_add_i32 s17, s16, 0x2000
	global_load_lds_dwordx4 v134, s[62:63]
	s_mov_b32 m0, s16
	v_lshl_add_u32 v132, v1, 12, v2
	global_load_lds_dwordx4 v128, s[60:61]
	s_mov_b32 m0, s17
	s_add_u32 s18, s62, 0x80000
	global_load_lds_dwordx4 v132, s[60:61]
	s_addc_u32 s19, s63, 0
	s_add_i32 m0, s16, 0x14000
	v_mov_b32_e32 v131, 0
	global_load_lds_dwordx4 v130, s[18:19]
	s_add_i32 m0, s16, 0x16000
	v_mov_b32_e32 v135, v131
	global_load_lds_dwordx4 v134, s[18:19]
	s_add_u32 s18, s60, 0x80000
	s_addc_u32 s19, s61, 0
	s_add_i32 s20, s16, 0x4000
	s_mov_b32 m0, s20
	s_add_i32 s21, s16, 0x6000
	global_load_lds_dwordx4 v128, s[18:19]
	s_mov_b32 m0, s21
	v_mov_b32_e32 v129, v131
	global_load_lds_dwordx4 v132, s[18:19]
	v_mov_b32_e32 v133, v131
	s_mov_b32 s42, 32
	s_mov_b32 s9, 0
	v_lshl_add_u64 v[6:7], s[62:63], 0, v[130:131]
	v_lshl_add_u64 v[4:5], s[62:63], 0, v[134:135]
	v_lshl_add_u64 v[0:1], s[60:61], 0, v[128:129]
	s_cmp_lg_u32 s15, 1
	v_lshl_add_u64 v[2:3], s[60:61], 0, v[132:133]
	s_cbranch_scc1 .LBB0_1045
	s_barrier
; #define PG8_STAGE(bufoff, gbase, voff) do { _Pragma("unroll") for (int _i = 0; _i < 2; ++_i) \
;         __builtin_amdgcn_global_load_lds((const unsigned*)((const char*)(gbase) + (voff)[_i]), (LAS unsigned*)(lds + (bufoff) + ldsw + _i * 8192), 16, 0, 0); } while (0)
; #define PG8_WAIT_V(n) asm volatile("s_waitcnt vmcnt(" #n ")" ::: "memory")
; #define PG8_BAR __builtin_amdgcn_s_barrier()
; template <class Epi, class S_t>
; __device__ __forceinline__ void gemm_phase(LAS unsigned char* lds, int lda, int ldb, const S_t& S, const Epi& E) {
;     ...
;     PG8_STAGE(PG8_SB(1, 0), cB + kstep, voffB); PG8_STAGE(PG8_SA(1, 0), cA + kstep, voffA); PG8_STAGE(PG8_SB(1, 1), cB + hstepB + kstep, voffB);
;     PG8_WAIT_V(6); PG8_BAR;
;     for (;;) {
;         const bool has_next = S.next(ui + 1, nxt);
;         const char* nA = has_next ? nxt.A : cA; const char* nB = has_next ? nxt.B : cB;
;         const int nt = cur.nt;
.LBB0_1045:
	s_lshl_b32 s12, s12, 5
	s_and_b32 s48, s12, 0x60
	s_mov_b64 s[12:13], 0x80
	s_add_i32 m0, s16, 0x18000
	v_lshl_add_u64 v[6:7], v[6:7], 0, s[12:13]
	s_lshl_b32 s33, s15, 13
	s_lshl_b32 s46, s48, 7
	s_waitcnt vmcnt(4)
	s_barrier
	global_load_lds_dwordx4 v[6:7], off
	v_lshl_add_u64 v[4:5], v[4:5], 0, s[12:13]
	s_add_i32 m0, s16, 0x1a000
	s_add_i32 s35, s16, 0x8000
	s_add_i32 s52, s16, 0xa000
	global_load_lds_dwordx4 v[4:5], off
	v_lshl_add_u64 v[0:1], v[0:1], 0, s[12:13]
	s_mov_b32 m0, s35
	s_add_u32 s18, s62, 0x80080
	global_load_lds_dwordx4 v[0:1], off
	v_lshl_add_u64 v[0:1], v[2:3], 0, s[12:13]
	s_mov_b32 m0, s52
	s_addc_u32 s19, s63, 0
	global_load_lds_dwordx4 v[0:1], off
	s_add_i32 m0, s16, 0x1c000
	v_lshl_add_u64 v[0:1], s[18:19], 0, v[130:131]
	global_load_lds_dwordx4 v[0:1], off
	v_lshl_add_u64 v[0:1], s[18:19], 0, v[134:135]
	s_add_i32 m0, s16, 0x1e000
	s_sext_i32_i8 s43, s14
	global_load_lds_dwordx4 v[0:1], off
	v_lshrrev_b32_e32 v1, 1, v11
	v_and_b32_e32 v1, 24, v1
	v_and_b32_e32 v0, 15, v11
	v_lshlrev_b32_e32 v2, 1, v1
	s_ashr_i32 s14, s2, 6
	v_lshl_or_b32 v142, s15, 6, v0
	v_lshl_or_b32 v0, v0, 6, v2
	v_lshlrev_b32_e32 v2, 2, v11
	s_add_i32 s14, s14, 32
	v_and_b32_e32 v2, 32, v2
	v_readlane_b32 s6, v255, 14
	s_ashr_i32 s15, s14, 31
	v_bitop3_b32 v3, v0, s33, v2 bitop3:0xde
	v_bitop3_b32 v143, v0, s46, v2 bitop3:0xde
	s_lshl_b32 s33, s6, 9
	s_bfe_u32 s53, s2, 0x30003
	s_add_i32 s64, s6, 1
	s_lshl_b64 s[18:19], s[14:15], 20
	v_lshlrev_b32_e32 v0, 15, v8
	s_add_u32 s15, s44, s18
	v_and_b32_e32 v0, 0xffff0000, v0
	s_addc_u32 s19, s45, s19
	v_or_b32_e32 v145, s48, v1
	v_lshl_add_u32 v0, v9, 12, v0
	v_and_b32_e32 v1, 1, v8
	s_add_u32 s18, s15, s33
	v_lshl_or_b32 v0, v1, 6, v0
	s_addc_u32 s19, s19, 0
	s_lshl_b32 s15, s53, 20
	v_lshl_add_u32 v136, v10, 1, v0
	v_lshlrev_b32_e32 v0, 15, v12
	s_add_u32 s0, s0, s15
	v_and_b32_e32 v0, 0xffff0000, v0
	s_waitcnt vmcnt(6)
	s_addc_u32 s1, s1, 0
	v_lshl_add_u32 v0, v13, 12, v0
	v_and_b32_e32 v1, 1, v12
	s_add_u32 s46, s0, s33
	v_lshl_or_b32 v0, v1, 6, v0
	v_add_u32_e32 v144, 0xffffe000, v142
	s_addc_u32 s47, s1, 0
	v_mov_b32_e32 v137, v131
	v_lshl_add_u32 v138, v14, 1, v0
	v_mov_b32_e32 v139, v131
	s_mov_b64 s[0:1], -1
	v_add_u32_e32 v146, s88, v143
	v_add_u32_e32 v147, 0, v3
	v_add_u32_e32 v148, s89, v143
	s_mov_b32 s15, 0xa0000
	s_mov_b64 s[48:49], 0xb0000
	s_mov_b32 s65, 0xb0000
	s_mov_b32 s68, 0
	s_barrier
	s_mov_b64 s[18:19], s[98:99]
	s_mov_b64 s[46:47], s[100:101]
	s_mov_b32 s42, 4
	s_mov_b32 s68, s64
	s_mov_b32 s98, s43
	s_mov_b32 s43, s53
	s_mov_b32 s53, s98
	s_mov_b32 s98, s8
	s_mov_b32 s8, s14
	s_mov_b32 s14, s98
	s_branch .LBB0_1048

; template <class Epi, class S_t>
; __device__ __forceinline__ void gemm_phase(LAS unsigned char* lds, int lda, int ldb, const S_t& S, const Epi& E) {
;     ...
;         if (!has_next) break;
; #pragma unroll
;         for (int a = 0; a < 2; ++a)
; #pragma unroll
;             for (int b = 0; b < 2; ++b)
; #pragma unroll
;                 for (int m = 0; m < 4; ++m)
; #pragma unroll
;                     for (int n = 0; n < 2; ++n) acc[a][b][m][n] = (f32x4){0.f, 0.f, 0.f, 0.f};
;         cur = nxt; cA = nA; cB = nB; ++ui;
.LBB0_1047:
	s_mov_b64 s[0:1], 0
	s_mov_b32 s42, 32
	s_and_b64 vcc, exec, s[54:55]
	s_mov_b32 s68, 0
	s_mov_b32 s43, s53
	s_mov_b32 s8, s14
	s_mov_b64 s[62:63], s[46:47]
	s_mov_b64 s[60:61], s[18:19]
	s_cbranch_vccnz .LBB0_1055
